# scan y output computed with two FMAs (drops mov, packed mul and an add per step)
# speedup vs baseline: 1.0073x; 1.0024x over previous
; #define SC_LOAD(t) { _Pragma("unroll") for (int q = 0; q < 5; ++q) { n[2 * q] = *(const LAS f32x4*)(opb + (t) * 320 + q * 64); n[2 * q + 1] = *(const LAS f32x4*)(opb + (t) * 320 + q * 64 + 4); } \
;                      nv = vvb[(t) * 64]; nbk = *(const LAS f32x2*)(scb + (t) * 4); }
; DI void scan_item(const __attribute__((address_space(4))) Args& a, LAS unsigned char* lds, int ws_, bool is_prompt, int seq, int h, int half, bool dry = false) {
;     ...
;         SC_LOAD(0)
; #pragma unroll 4
;         for (int t = 0; t < SC_CH; ++t) {
;             f32x4 c[10];
; #pragma unroll
;             for (int q = 0; q < 10; ++q) c[q] = n[q];
;             const float v0 = nv; const f32x2 bk = nbk;
;             SC_LOAD(t + 1)
;             __builtin_amdgcn_sched_barrier(0);
;             f32x2 aA = sp[0] * c[0].xy, aY = sp[0] * c[2].xy;
;             aA = sp[1] * c[0].zw + aA; aY = sp[1] * c[2].zw + aY;
;             aA = sp[2] * c[1].xy + aA; aY = sp[2] * c[3].xy + aY;
;             aA = sp[3] * c[1].zw + aA; aY = sp[3] * c[3].zw + aY;
;             float da = aA.x + aA.y, dy = aY.x + aY.y;
;             asm("s_nop 1\n\t"
;                 "v_add_f32_dpp %0, %0, %0 quad_perm:[1,0,3,2] row_mask:0xf bank_mask:0xf bound_ctrl:1\n\t"
;                 "v_add_f32_dpp %1, %1, %1 quad_perm:[1,0,3,2] row_mask:0xf bank_mask:0xf bound_ctrl:1\n\t"
;                 "s_nop 0\n\t"
;                 "v_add_f32_dpp %0, %0, %0 quad_perm:[2,3,0,1] row_mask:0xf bank_mask:0xf bound_ctrl:1\n\t"
;                 "v_add_f32_dpp %1, %1, %1 quad_perm:[2,3,0,1] row_mask:0xf bank_mask:0xf bound_ctrl:1\n\t"
;                 "s_nop 0\n\t"
;                 "v_add_f32_dpp %0, %0, %0 row_half_mirror row_mask:0xf bank_mask:0xf bound_ctrl:1\n\t"
;                 "v_add_f32_dpp %1, %1, %1 row_half_mirror row_mask:0xf bank_mask:0xf bound_ctrl:1"
;                 : "+v"(da), "+v"(dy));
;             {
;                 f32x2 t0;
;                 t0 = c[8].xy * v0; t0 = c[6].xy * da + t0; sp[0] = sp[0] * c[4].xy + t0;
;                 t0 = c[8].zw * v0; t0 = c[6].zw * da + t0; sp[1] = sp[1] * c[4].zw + t0;
;                 t0 = c[9].xy * v0; t0 = c[7].xy * da + t0; sp[2] = sp[2] * c[5].xy + t0;
;                 t0 = c[9].zw * v0; t0 = c[7].zw * da + t0; sp[3] = sp[3] * c[5].zw + t0;
;             }
;             ybb[t * 32] = dy + da * bk.x + v0 * bk.y;
;         }
.LBB0_1535:
	s_and_b64 vcc, exec, s[74:75]
	s_cbranch_vccz .LBB0_1523
	s_bitcmp1_b32 s24, 0
	s_cselect_b32 s34, 0x6900, 0
	s_add_i32 s35, s34, 0
	s_waitcnt vmcnt(0)
	v_lshl_add_u32 v120, v110, 2, s35
	v_lshl_add_u32 v96, v111, 2, s35
	v_lshl_add_u32 v136, v115, 2, s35
	v_mov_b32_e32 v121, s35
	v_add_u32_e32 v136, 0x6100, v136
	v_cndmask_b32_e64 v95, v116, v136, s[8:9]
	ds_read_b128 v[40:43], v120
	ds_read_b128 v[44:47], v120 offset:16
	ds_read_b128 v[48:51], v120 offset:256
	ds_read_b128 v[52:55], v120 offset:272
	ds_read_b128 v[56:59], v120 offset:512
	ds_read_b128 v[60:63], v120 offset:528
	ds_read_b128 v[64:67], v120 offset:768
	ds_read_b128 v[68:71], v120 offset:784
	ds_read_b128 v[72:75], v120 offset:1024
	ds_read_b128 v[76:79], v120 offset:1040
	ds_read_b32 v94, v96 offset:20480
	ds_read_b64 v[108:109], v121 offset:24576
	ds_read_b128 v[190:193], v120 offset:1280
	ds_read_b128 v[194:197], v120 offset:1296
	ds_read_b128 v[198:201], v120 offset:1536
	ds_read_b128 v[202:205], v120 offset:1552
	ds_read_b128 v[206:209], v120 offset:1792
	ds_read_b128 v[210:213], v120 offset:1808
	ds_read_b128 v[214:217], v120 offset:2048
	ds_read_b128 v[218:221], v120 offset:2064
	ds_read_b128 v[222:225], v120 offset:2304
	ds_read_b128 v[226:229], v120 offset:2320
	ds_read_b32 v230, v96 offset:20736
	ds_read_b64 v[232:233], v121 offset:24592
	s_waitcnt lgkmcnt(12)
	v_pk_mul_f32 v[122:123], v[38:39], v[42:43]
	v_pk_mul_f32 v[124:125], v[38:39], v[50:51]
	v_pk_fma_f32 v[122:123], v[36:37], v[40:41], v[122:123]
	v_pk_fma_f32 v[124:125], v[36:37], v[48:49], v[124:125]
	v_pk_fma_f32 v[122:123], v[32:33], v[44:45], v[122:123]
	v_pk_fma_f32 v[124:125], v[32:33], v[52:53], v[124:125]
	v_pk_fma_f32 v[122:123], v[34:35], v[46:47], v[122:123]
	v_pk_fma_f32 v[124:125], v[34:35], v[54:55], v[124:125]
	v_pk_mul_f32 v[126:127], v[72:73], v[94:95] op_sel_hi:[1,0]
	v_add_f32_e32 v166, v122, v123
	v_add_f32_e32 v168, v124, v125
	v_pk_mul_f32 v[128:129], v[74:75], v[94:95] op_sel_hi:[1,0]
	v_pk_mul_f32 v[130:131], v[76:77], v[94:95] op_sel_hi:[1,0]
	v_add_f32_dpp v166, v166, v166 quad_perm:[1,0,3,2] row_mask:0xf bank_mask:0xf bound_ctrl:1
	v_add_f32_dpp v168, v168, v168 quad_perm:[1,0,3,2] row_mask:0xf bank_mask:0xf bound_ctrl:1
	v_pk_mul_f32 v[132:133], v[78:79], v[94:95] op_sel_hi:[1,0]
	v_pk_fma_f32 v[126:127], v[36:37], v[56:57], v[126:127]
	v_add_f32_dpp v166, v166, v166 quad_perm:[2,3,0,1] row_mask:0xf bank_mask:0xf bound_ctrl:1
	v_add_f32_dpp v168, v168, v168 quad_perm:[2,3,0,1] row_mask:0xf bank_mask:0xf bound_ctrl:1
	v_pk_fma_f32 v[128:129], v[38:39], v[58:59], v[128:129]
	v_pk_fma_f32 v[130:131], v[32:33], v[60:61], v[130:131]
	v_add_f32_dpp v166, v166, v166 row_half_mirror row_mask:0xf bank_mask:0xf bound_ctrl:1
	v_add_f32_dpp v168, v168, v168 row_half_mirror row_mask:0xf bank_mask:0xf bound_ctrl:1
	v_pk_fma_f32 v[132:133], v[34:35], v[62:63], v[132:133]
	v_fma_f32 v136, v166, v108, v168
	v_pk_fma_f32 v[36:37], v[64:65], v[166:167], v[126:127] op_sel_hi:[1,0,1]
	v_pk_fma_f32 v[38:39], v[66:67], v[166:167], v[128:129] op_sel_hi:[1,0,1]
	v_pk_fma_f32 v[32:33], v[68:69], v[166:167], v[130:131] op_sel_hi:[1,0,1]
	v_pk_fma_f32 v[34:35], v[70:71], v[166:167], v[132:133] op_sel_hi:[1,0,1]
	v_fma_f32 v136, v94, v109, v136
	ds_write_b32 v95, v136
	ds_read_b128 v[40:43], v120 offset:2560
	ds_read_b128 v[44:47], v120 offset:2576
	ds_read_b128 v[48:51], v120 offset:2816
	ds_read_b128 v[52:55], v120 offset:2832
	ds_read_b128 v[56:59], v120 offset:3072
	ds_read_b128 v[60:63], v120 offset:3088
	ds_read_b128 v[64:67], v120 offset:3328
	ds_read_b128 v[68:71], v120 offset:3344
	ds_read_b128 v[72:75], v120 offset:3584
	ds_read_b128 v[76:79], v120 offset:3600
	ds_read_b32 v94, v96 offset:20992
	ds_read_b64 v[108:109], v121 offset:24608
	s_waitcnt lgkmcnt(12)
	v_pk_mul_f32 v[122:123], v[38:39], v[192:193]
	v_pk_mul_f32 v[124:125], v[38:39], v[200:201]
	v_pk_fma_f32 v[122:123], v[36:37], v[190:191], v[122:123]
	v_pk_fma_f32 v[124:125], v[36:37], v[198:199], v[124:125]
	v_pk_fma_f32 v[122:123], v[32:33], v[194:195], v[122:123]
	v_pk_fma_f32 v[124:125], v[32:33], v[202:203], v[124:125]
	v_pk_fma_f32 v[122:123], v[34:35], v[196:197], v[122:123]
	v_pk_fma_f32 v[124:125], v[34:35], v[204:205], v[124:125]
	v_pk_mul_f32 v[126:127], v[222:223], v[230:231] op_sel_hi:[1,0]
	v_add_f32_e32 v166, v122, v123
	v_add_f32_e32 v168, v124, v125
	v_pk_mul_f32 v[128:129], v[224:225], v[230:231] op_sel_hi:[1,0]
	v_pk_mul_f32 v[130:131], v[226:227], v[230:231] op_sel_hi:[1,0]
	v_add_f32_dpp v166, v166, v166 quad_perm:[1,0,3,2] row_mask:0xf bank_mask:0xf bound_ctrl:1
	v_add_f32_dpp v168, v168, v168 quad_perm:[1,0,3,2] row_mask:0xf bank_mask:0xf bound_ctrl:1
	v_pk_mul_f32 v[132:133], v[228:229], v[230:231] op_sel_hi:[1,0]
	v_pk_fma_f32 v[126:127], v[36:37], v[206:207], v[126:127]
	v_add_f32_dpp v166, v166, v166 quad_perm:[2,3,0,1] row_mask:0xf bank_mask:0xf bound_ctrl:1
	v_add_f32_dpp v168, v168, v168 quad_perm:[2,3,0,1] row_mask:0xf bank_mask:0xf bound_ctrl:1
	v_pk_fma_f32 v[128:129], v[38:39], v[208:209], v[128:129]
	v_pk_fma_f32 v[130:131], v[32:33], v[210:211], v[130:131]
	v_add_f32_dpp v166, v166, v166 row_half_mirror row_mask:0xf bank_mask:0xf bound_ctrl:1
	v_add_f32_dpp v168, v168, v168 row_half_mirror row_mask:0xf bank_mask:0xf bound_ctrl:1
	v_pk_fma_f32 v[132:133], v[34:35], v[212:213], v[132:133]
	v_fma_f32 v136, v166, v232, v168
	v_pk_fma_f32 v[36:37], v[214:215], v[166:167], v[126:127] op_sel_hi:[1,0,1]
	v_pk_fma_f32 v[38:39], v[216:217], v[166:167], v[128:129] op_sel_hi:[1,0,1]
	v_pk_fma_f32 v[32:33], v[218:219], v[166:167], v[130:131] op_sel_hi:[1,0,1]
	v_pk_fma_f32 v[34:35], v[220:221], v[166:167], v[132:133] op_sel_hi:[1,0,1]
	v_fma_f32 v136, v230, v233, v136
	ds_write_b32 v95, v136 offset:128
	ds_read_b128 v[190:193], v120 offset:3840
	ds_read_b128 v[194:197], v120 offset:3856
	ds_read_b128 v[198:201], v120 offset:4096
	ds_read_b128 v[202:205], v120 offset:4112
	ds_read_b128 v[206:209], v120 offset:4352
	ds_read_b128 v[210:213], v120 offset:4368
	ds_read_b128 v[214:217], v120 offset:4608
	ds_read_b128 v[218:221], v120 offset:4624
	ds_read_b128 v[222:225], v120 offset:4864
	ds_read_b128 v[226:229], v120 offset:4880
	ds_read_b32 v230, v96 offset:21248
	ds_read_b64 v[232:233], v121 offset:24624
	s_waitcnt lgkmcnt(12)
; #define SC_LOAD(t) { _Pragma("unroll") for (int q = 0; q < 5; ++q) { n[2 * q] = *(const LAS f32x4*)(opb + (t) * 320 + q * 64); n[2 * q + 1] = *(const LAS f32x4*)(opb + (t) * 320 + q * 64 + 4); } \
;                      nv = vvb[(t) * 64]; nbk = *(const LAS f32x2*)(scb + (t) * 4); }
; DI void scan_item(const __attribute__((address_space(4))) Args& a, LAS unsigned char* lds, int ws_, bool is_prompt, int seq, int h, int half, bool dry = false) {
;     ...
;         SC_LOAD(0)
; #pragma unroll 4
;         for (int t = 0; t < SC_CH; ++t) {
;             f32x4 c[10];
; #pragma unroll
;             for (int q = 0; q < 10; ++q) c[q] = n[q];
;             const float v0 = nv; const f32x2 bk = nbk;
;             SC_LOAD(t + 1)
;             __builtin_amdgcn_sched_barrier(0);
;             f32x2 aA = sp[0] * c[0].xy, aY = sp[0] * c[2].xy;
;             aA = sp[1] * c[0].zw + aA; aY = sp[1] * c[2].zw + aY;
;             aA = sp[2] * c[1].xy + aA; aY = sp[2] * c[3].xy + aY;
;             aA = sp[3] * c[1].zw + aA; aY = sp[3] * c[3].zw + aY;
;             float da = aA.x + aA.y, dy = aY.x + aY.y;
;             asm("s_nop 1\n\t"
;                 "v_add_f32_dpp %0, %0, %0 quad_perm:[1,0,3,2] row_mask:0xf bank_mask:0xf bound_ctrl:1\n\t"
;                 "v_add_f32_dpp %1, %1, %1 quad_perm:[1,0,3,2] row_mask:0xf bank_mask:0xf bound_ctrl:1\n\t"
;                 "s_nop 0\n\t"
;                 "v_add_f32_dpp %0, %0, %0 quad_perm:[2,3,0,1] row_mask:0xf bank_mask:0xf bound_ctrl:1\n\t"
;                 "v_add_f32_dpp %1, %1, %1 quad_perm:[2,3,0,1] row_mask:0xf bank_mask:0xf bound_ctrl:1\n\t"
;                 "s_nop 0\n\t"
;                 "v_add_f32_dpp %0, %0, %0 row_half_mirror row_mask:0xf bank_mask:0xf bound_ctrl:1\n\t"
;                 "v_add_f32_dpp %1, %1, %1 row_half_mirror row_mask:0xf bank_mask:0xf bound_ctrl:1"
;                 : "+v"(da), "+v"(dy));
;             {
;                 f32x2 t0;
;                 t0 = c[8].xy * v0; t0 = c[6].xy * da + t0; sp[0] = sp[0] * c[4].xy + t0;
;                 t0 = c[8].zw * v0; t0 = c[6].zw * da + t0; sp[1] = sp[1] * c[4].zw + t0;
;                 t0 = c[9].xy * v0; t0 = c[7].xy * da + t0; sp[2] = sp[2] * c[5].xy + t0;
;                 t0 = c[9].zw * v0; t0 = c[7].zw * da + t0; sp[3] = sp[3] * c[5].zw + t0;
;             }
;             ybb[t * 32] = dy + da * bk.x + v0 * bk.y;
;         }
	v_pk_mul_f32 v[122:123], v[38:39], v[42:43]
	v_pk_mul_f32 v[124:125], v[38:39], v[50:51]
	v_pk_fma_f32 v[122:123], v[36:37], v[40:41], v[122:123]
	v_pk_fma_f32 v[124:125], v[36:37], v[48:49], v[124:125]
	v_pk_fma_f32 v[122:123], v[32:33], v[44:45], v[122:123]
	v_pk_fma_f32 v[124:125], v[32:33], v[52:53], v[124:125]
	v_pk_fma_f32 v[122:123], v[34:35], v[46:47], v[122:123]
	v_pk_fma_f32 v[124:125], v[34:35], v[54:55], v[124:125]
	v_pk_mul_f32 v[126:127], v[72:73], v[94:95] op_sel_hi:[1,0]
	v_add_f32_e32 v166, v122, v123
	v_add_f32_e32 v168, v124, v125
	v_pk_mul_f32 v[128:129], v[74:75], v[94:95] op_sel_hi:[1,0]
	v_pk_mul_f32 v[130:131], v[76:77], v[94:95] op_sel_hi:[1,0]
	v_add_f32_dpp v166, v166, v166 quad_perm:[1,0,3,2] row_mask:0xf bank_mask:0xf bound_ctrl:1
	v_add_f32_dpp v168, v168, v168 quad_perm:[1,0,3,2] row_mask:0xf bank_mask:0xf bound_ctrl:1
	v_pk_mul_f32 v[132:133], v[78:79], v[94:95] op_sel_hi:[1,0]
	v_pk_fma_f32 v[126:127], v[36:37], v[56:57], v[126:127]
	v_add_f32_dpp v166, v166, v166 quad_perm:[2,3,0,1] row_mask:0xf bank_mask:0xf bound_ctrl:1
	v_add_f32_dpp v168, v168, v168 quad_perm:[2,3,0,1] row_mask:0xf bank_mask:0xf bound_ctrl:1
	v_pk_fma_f32 v[128:129], v[38:39], v[58:59], v[128:129]
	v_pk_fma_f32 v[130:131], v[32:33], v[60:61], v[130:131]
	v_add_f32_dpp v166, v166, v166 row_half_mirror row_mask:0xf bank_mask:0xf bound_ctrl:1
	v_add_f32_dpp v168, v168, v168 row_half_mirror row_mask:0xf bank_mask:0xf bound_ctrl:1
	v_pk_fma_f32 v[132:133], v[34:35], v[62:63], v[132:133]
	v_fma_f32 v136, v166, v108, v168
	v_pk_fma_f32 v[36:37], v[64:65], v[166:167], v[126:127] op_sel_hi:[1,0,1]
	v_pk_fma_f32 v[38:39], v[66:67], v[166:167], v[128:129] op_sel_hi:[1,0,1]
	v_pk_fma_f32 v[32:33], v[68:69], v[166:167], v[130:131] op_sel_hi:[1,0,1]
	v_pk_fma_f32 v[34:35], v[70:71], v[166:167], v[132:133] op_sel_hi:[1,0,1]
	v_fma_f32 v136, v94, v109, v136
	ds_write_b32 v95, v136 offset:256
	ds_read_b128 v[40:43], v120 offset:5120
	ds_read_b128 v[44:47], v120 offset:5136
	ds_read_b128 v[48:51], v120 offset:5376
	ds_read_b128 v[52:55], v120 offset:5392
	ds_read_b128 v[56:59], v120 offset:5632
	ds_read_b128 v[60:63], v120 offset:5648
	ds_read_b128 v[64:67], v120 offset:5888
	ds_read_b128 v[68:71], v120 offset:5904
	ds_read_b128 v[72:75], v120 offset:6144
	ds_read_b128 v[76:79], v120 offset:6160
	ds_read_b32 v94, v96 offset:21504
	ds_read_b64 v[108:109], v121 offset:24640
	s_waitcnt lgkmcnt(12)
	v_pk_mul_f32 v[122:123], v[38:39], v[192:193]
	v_pk_mul_f32 v[124:125], v[38:39], v[200:201]
	v_pk_fma_f32 v[122:123], v[36:37], v[190:191], v[122:123]
	v_pk_fma_f32 v[124:125], v[36:37], v[198:199], v[124:125]
	v_pk_fma_f32 v[122:123], v[32:33], v[194:195], v[122:123]
	v_pk_fma_f32 v[124:125], v[32:33], v[202:203], v[124:125]
	v_pk_fma_f32 v[122:123], v[34:35], v[196:197], v[122:123]
	v_pk_fma_f32 v[124:125], v[34:35], v[204:205], v[124:125]
	v_pk_mul_f32 v[126:127], v[222:223], v[230:231] op_sel_hi:[1,0]
	v_add_f32_e32 v166, v122, v123
	v_add_f32_e32 v168, v124, v125
	v_pk_mul_f32 v[128:129], v[224:225], v[230:231] op_sel_hi:[1,0]
	v_pk_mul_f32 v[130:131], v[226:227], v[230:231] op_sel_hi:[1,0]
	v_add_f32_dpp v166, v166, v166 quad_perm:[1,0,3,2] row_mask:0xf bank_mask:0xf bound_ctrl:1
	v_add_f32_dpp v168, v168, v168 quad_perm:[1,0,3,2] row_mask:0xf bank_mask:0xf bound_ctrl:1
	v_pk_mul_f32 v[132:133], v[228:229], v[230:231] op_sel_hi:[1,0]
	v_pk_fma_f32 v[126:127], v[36:37], v[206:207], v[126:127]
	v_add_f32_dpp v166, v166, v166 quad_perm:[2,3,0,1] row_mask:0xf bank_mask:0xf bound_ctrl:1
	v_add_f32_dpp v168, v168, v168 quad_perm:[2,3,0,1] row_mask:0xf bank_mask:0xf bound_ctrl:1
	v_pk_fma_f32 v[128:129], v[38:39], v[208:209], v[128:129]
	v_pk_fma_f32 v[130:131], v[32:33], v[210:211], v[130:131]
	v_add_f32_dpp v166, v166, v166 row_half_mirror row_mask:0xf bank_mask:0xf bound_ctrl:1
	v_add_f32_dpp v168, v168, v168 row_half_mirror row_mask:0xf bank_mask:0xf bound_ctrl:1
	v_pk_fma_f32 v[132:133], v[34:35], v[212:213], v[132:133]
	v_fma_f32 v136, v166, v232, v168
	v_pk_fma_f32 v[36:37], v[214:215], v[166:167], v[126:127] op_sel_hi:[1,0,1]
	v_pk_fma_f32 v[38:39], v[216:217], v[166:167], v[128:129] op_sel_hi:[1,0,1]
	v_pk_fma_f32 v[32:33], v[218:219], v[166:167], v[130:131] op_sel_hi:[1,0,1]
	v_pk_fma_f32 v[34:35], v[220:221], v[166:167], v[132:133] op_sel_hi:[1,0,1]
	v_fma_f32 v136, v230, v233, v136
	ds_write_b32 v95, v136 offset:384
	ds_read_b128 v[190:193], v120 offset:6400
	ds_read_b128 v[194:197], v120 offset:6416
	ds_read_b128 v[198:201], v120 offset:6656
	ds_read_b128 v[202:205], v120 offset:6672
	ds_read_b128 v[206:209], v120 offset:6912
	ds_read_b128 v[210:213], v120 offset:6928
	ds_read_b128 v[214:217], v120 offset:7168
	ds_read_b128 v[218:221], v120 offset:7184
	ds_read_b128 v[222:225], v120 offset:7424
	ds_read_b128 v[226:229], v120 offset:7440
	ds_read_b32 v230, v96 offset:21760
	ds_read_b64 v[232:233], v121 offset:24656
	s_waitcnt lgkmcnt(12)
; #define SC_LOAD(t) { _Pragma("unroll") for (int q = 0; q < 5; ++q) { n[2 * q] = *(const LAS f32x4*)(opb + (t) * 320 + q * 64); n[2 * q + 1] = *(const LAS f32x4*)(opb + (t) * 320 + q * 64 + 4); } \
;                      nv = vvb[(t) * 64]; nbk = *(const LAS f32x2*)(scb + (t) * 4); }
; DI void scan_item(const __attribute__((address_space(4))) Args& a, LAS unsigned char* lds, int ws_, bool is_prompt, int seq, int h, int half, bool dry = false) {
;     ...
;         SC_LOAD(0)
; #pragma unroll 4
;         for (int t = 0; t < SC_CH; ++t) {
;             f32x4 c[10];
; #pragma unroll
;             for (int q = 0; q < 10; ++q) c[q] = n[q];
;             const float v0 = nv; const f32x2 bk = nbk;
;             SC_LOAD(t + 1)
;             __builtin_amdgcn_sched_barrier(0);
;             f32x2 aA = sp[0] * c[0].xy, aY = sp[0] * c[2].xy;
;             aA = sp[1] * c[0].zw + aA; aY = sp[1] * c[2].zw + aY;
;             aA = sp[2] * c[1].xy + aA; aY = sp[2] * c[3].xy + aY;
;             aA = sp[3] * c[1].zw + aA; aY = sp[3] * c[3].zw + aY;
;             float da = aA.x + aA.y, dy = aY.x + aY.y;
;             asm("s_nop 1\n\t"
;                 "v_add_f32_dpp %0, %0, %0 quad_perm:[1,0,3,2] row_mask:0xf bank_mask:0xf bound_ctrl:1\n\t"
;                 "v_add_f32_dpp %1, %1, %1 quad_perm:[1,0,3,2] row_mask:0xf bank_mask:0xf bound_ctrl:1\n\t"
;                 "s_nop 0\n\t"
;                 "v_add_f32_dpp %0, %0, %0 quad_perm:[2,3,0,1] row_mask:0xf bank_mask:0xf bound_ctrl:1\n\t"
;                 "v_add_f32_dpp %1, %1, %1 quad_perm:[2,3,0,1] row_mask:0xf bank_mask:0xf bound_ctrl:1\n\t"
;                 "s_nop 0\n\t"
;                 "v_add_f32_dpp %0, %0, %0 row_half_mirror row_mask:0xf bank_mask:0xf bound_ctrl:1\n\t"
;                 "v_add_f32_dpp %1, %1, %1 row_half_mirror row_mask:0xf bank_mask:0xf bound_ctrl:1"
;                 : "+v"(da), "+v"(dy));
;             {
;                 f32x2 t0;
;                 t0 = c[8].xy * v0; t0 = c[6].xy * da + t0; sp[0] = sp[0] * c[4].xy + t0;
;                 t0 = c[8].zw * v0; t0 = c[6].zw * da + t0; sp[1] = sp[1] * c[4].zw + t0;
;                 t0 = c[9].xy * v0; t0 = c[7].xy * da + t0; sp[2] = sp[2] * c[5].xy + t0;
;                 t0 = c[9].zw * v0; t0 = c[7].zw * da + t0; sp[3] = sp[3] * c[5].zw + t0;
;             }
;             ybb[t * 32] = dy + da * bk.x + v0 * bk.y;
;         }
	v_pk_mul_f32 v[122:123], v[38:39], v[42:43]
	v_pk_mul_f32 v[124:125], v[38:39], v[50:51]
	v_pk_fma_f32 v[122:123], v[36:37], v[40:41], v[122:123]
	v_pk_fma_f32 v[124:125], v[36:37], v[48:49], v[124:125]
	v_pk_fma_f32 v[122:123], v[32:33], v[44:45], v[122:123]
	v_pk_fma_f32 v[124:125], v[32:33], v[52:53], v[124:125]
	v_pk_fma_f32 v[122:123], v[34:35], v[46:47], v[122:123]
	v_pk_fma_f32 v[124:125], v[34:35], v[54:55], v[124:125]
	v_pk_mul_f32 v[126:127], v[72:73], v[94:95] op_sel_hi:[1,0]
	v_add_f32_e32 v166, v122, v123
	v_add_f32_e32 v168, v124, v125
	v_pk_mul_f32 v[128:129], v[74:75], v[94:95] op_sel_hi:[1,0]
	v_pk_mul_f32 v[130:131], v[76:77], v[94:95] op_sel_hi:[1,0]
	v_add_f32_dpp v166, v166, v166 quad_perm:[1,0,3,2] row_mask:0xf bank_mask:0xf bound_ctrl:1
	v_add_f32_dpp v168, v168, v168 quad_perm:[1,0,3,2] row_mask:0xf bank_mask:0xf bound_ctrl:1
	v_pk_mul_f32 v[132:133], v[78:79], v[94:95] op_sel_hi:[1,0]
	v_pk_fma_f32 v[126:127], v[36:37], v[56:57], v[126:127]
	v_add_f32_dpp v166, v166, v166 quad_perm:[2,3,0,1] row_mask:0xf bank_mask:0xf bound_ctrl:1
	v_add_f32_dpp v168, v168, v168 quad_perm:[2,3,0,1] row_mask:0xf bank_mask:0xf bound_ctrl:1
	v_pk_fma_f32 v[128:129], v[38:39], v[58:59], v[128:129]
	v_pk_fma_f32 v[130:131], v[32:33], v[60:61], v[130:131]
	v_add_f32_dpp v166, v166, v166 row_half_mirror row_mask:0xf bank_mask:0xf bound_ctrl:1
	v_add_f32_dpp v168, v168, v168 row_half_mirror row_mask:0xf bank_mask:0xf bound_ctrl:1
	v_pk_fma_f32 v[132:133], v[34:35], v[62:63], v[132:133]
	v_fma_f32 v136, v166, v108, v168
	v_pk_fma_f32 v[36:37], v[64:65], v[166:167], v[126:127] op_sel_hi:[1,0,1]
	v_pk_fma_f32 v[38:39], v[66:67], v[166:167], v[128:129] op_sel_hi:[1,0,1]
	v_pk_fma_f32 v[32:33], v[68:69], v[166:167], v[130:131] op_sel_hi:[1,0,1]
	v_pk_fma_f32 v[34:35], v[70:71], v[166:167], v[132:133] op_sel_hi:[1,0,1]
	v_fma_f32 v136, v94, v109, v136
	ds_write_b32 v95, v136 offset:512
	ds_read_b128 v[40:43], v120 offset:7680
	ds_read_b128 v[44:47], v120 offset:7696
	ds_read_b128 v[48:51], v120 offset:7936
	ds_read_b128 v[52:55], v120 offset:7952
	ds_read_b128 v[56:59], v120 offset:8192
	ds_read_b128 v[60:63], v120 offset:8208
	ds_read_b128 v[64:67], v120 offset:8448
	ds_read_b128 v[68:71], v120 offset:8464
	ds_read_b128 v[72:75], v120 offset:8704
	ds_read_b128 v[76:79], v120 offset:8720
	ds_read_b32 v94, v96 offset:22016
	ds_read_b64 v[108:109], v121 offset:24672
	s_waitcnt lgkmcnt(12)
	v_pk_mul_f32 v[122:123], v[38:39], v[192:193]
	v_pk_mul_f32 v[124:125], v[38:39], v[200:201]
	v_pk_fma_f32 v[122:123], v[36:37], v[190:191], v[122:123]
	v_pk_fma_f32 v[124:125], v[36:37], v[198:199], v[124:125]
	v_pk_fma_f32 v[122:123], v[32:33], v[194:195], v[122:123]
	v_pk_fma_f32 v[124:125], v[32:33], v[202:203], v[124:125]
	v_pk_fma_f32 v[122:123], v[34:35], v[196:197], v[122:123]
	v_pk_fma_f32 v[124:125], v[34:35], v[204:205], v[124:125]
	v_pk_mul_f32 v[126:127], v[222:223], v[230:231] op_sel_hi:[1,0]
	v_add_f32_e32 v166, v122, v123
	v_add_f32_e32 v168, v124, v125
	v_pk_mul_f32 v[128:129], v[224:225], v[230:231] op_sel_hi:[1,0]
	v_pk_mul_f32 v[130:131], v[226:227], v[230:231] op_sel_hi:[1,0]
	v_add_f32_dpp v166, v166, v166 quad_perm:[1,0,3,2] row_mask:0xf bank_mask:0xf bound_ctrl:1
	v_add_f32_dpp v168, v168, v168 quad_perm:[1,0,3,2] row_mask:0xf bank_mask:0xf bound_ctrl:1
	v_pk_mul_f32 v[132:133], v[228:229], v[230:231] op_sel_hi:[1,0]
	v_pk_fma_f32 v[126:127], v[36:37], v[206:207], v[126:127]
	v_add_f32_dpp v166, v166, v166 quad_perm:[2,3,0,1] row_mask:0xf bank_mask:0xf bound_ctrl:1
	v_add_f32_dpp v168, v168, v168 quad_perm:[2,3,0,1] row_mask:0xf bank_mask:0xf bound_ctrl:1
	v_pk_fma_f32 v[128:129], v[38:39], v[208:209], v[128:129]
	v_pk_fma_f32 v[130:131], v[32:33], v[210:211], v[130:131]
	v_add_f32_dpp v166, v166, v166 row_half_mirror row_mask:0xf bank_mask:0xf bound_ctrl:1
	v_add_f32_dpp v168, v168, v168 row_half_mirror row_mask:0xf bank_mask:0xf bound_ctrl:1
	v_pk_fma_f32 v[132:133], v[34:35], v[212:213], v[132:133]
	v_fma_f32 v136, v166, v232, v168
	v_pk_fma_f32 v[36:37], v[214:215], v[166:167], v[126:127] op_sel_hi:[1,0,1]
	v_pk_fma_f32 v[38:39], v[216:217], v[166:167], v[128:129] op_sel_hi:[1,0,1]
	v_pk_fma_f32 v[32:33], v[218:219], v[166:167], v[130:131] op_sel_hi:[1,0,1]
	v_pk_fma_f32 v[34:35], v[220:221], v[166:167], v[132:133] op_sel_hi:[1,0,1]
	v_fma_f32 v136, v230, v233, v136
	ds_write_b32 v95, v136 offset:640
	ds_read_b128 v[190:193], v120 offset:8960
	ds_read_b128 v[194:197], v120 offset:8976
	ds_read_b128 v[198:201], v120 offset:9216
	ds_read_b128 v[202:205], v120 offset:9232
	ds_read_b128 v[206:209], v120 offset:9472
	ds_read_b128 v[210:213], v120 offset:9488
	ds_read_b128 v[214:217], v120 offset:9728
	ds_read_b128 v[218:221], v120 offset:9744
	ds_read_b128 v[222:225], v120 offset:9984
	ds_read_b128 v[226:229], v120 offset:10000
	ds_read_b32 v230, v96 offset:22272
	ds_read_b64 v[232:233], v121 offset:24688
	s_waitcnt lgkmcnt(12)
; #define SC_LOAD(t) { _Pragma("unroll") for (int q = 0; q < 5; ++q) { n[2 * q] = *(const LAS f32x4*)(opb + (t) * 320 + q * 64); n[2 * q + 1] = *(const LAS f32x4*)(opb + (t) * 320 + q * 64 + 4); } \
;                      nv = vvb[(t) * 64]; nbk = *(const LAS f32x2*)(scb + (t) * 4); }
; DI void scan_item(const __attribute__((address_space(4))) Args& a, LAS unsigned char* lds, int ws_, bool is_prompt, int seq, int h, int half, bool dry = false) {
;     ...
;         SC_LOAD(0)
; #pragma unroll 4
;         for (int t = 0; t < SC_CH; ++t) {
;             f32x4 c[10];
; #pragma unroll
;             for (int q = 0; q < 10; ++q) c[q] = n[q];
;             const float v0 = nv; const f32x2 bk = nbk;
;             SC_LOAD(t + 1)
;             __builtin_amdgcn_sched_barrier(0);
;             f32x2 aA = sp[0] * c[0].xy, aY = sp[0] * c[2].xy;
;             aA = sp[1] * c[0].zw + aA; aY = sp[1] * c[2].zw + aY;
;             aA = sp[2] * c[1].xy + aA; aY = sp[2] * c[3].xy + aY;
;             aA = sp[3] * c[1].zw + aA; aY = sp[3] * c[3].zw + aY;
;             float da = aA.x + aA.y, dy = aY.x + aY.y;
;             asm("s_nop 1\n\t"
;                 "v_add_f32_dpp %0, %0, %0 quad_perm:[1,0,3,2] row_mask:0xf bank_mask:0xf bound_ctrl:1\n\t"
;                 "v_add_f32_dpp %1, %1, %1 quad_perm:[1,0,3,2] row_mask:0xf bank_mask:0xf bound_ctrl:1\n\t"
;                 "s_nop 0\n\t"
;                 "v_add_f32_dpp %0, %0, %0 quad_perm:[2,3,0,1] row_mask:0xf bank_mask:0xf bound_ctrl:1\n\t"
;                 "v_add_f32_dpp %1, %1, %1 quad_perm:[2,3,0,1] row_mask:0xf bank_mask:0xf bound_ctrl:1\n\t"
;                 "s_nop 0\n\t"
;                 "v_add_f32_dpp %0, %0, %0 row_half_mirror row_mask:0xf bank_mask:0xf bound_ctrl:1\n\t"
;                 "v_add_f32_dpp %1, %1, %1 row_half_mirror row_mask:0xf bank_mask:0xf bound_ctrl:1"
;                 : "+v"(da), "+v"(dy));
;             {
;                 f32x2 t0;
;                 t0 = c[8].xy * v0; t0 = c[6].xy * da + t0; sp[0] = sp[0] * c[4].xy + t0;
;                 t0 = c[8].zw * v0; t0 = c[6].zw * da + t0; sp[1] = sp[1] * c[4].zw + t0;
;                 t0 = c[9].xy * v0; t0 = c[7].xy * da + t0; sp[2] = sp[2] * c[5].xy + t0;
;                 t0 = c[9].zw * v0; t0 = c[7].zw * da + t0; sp[3] = sp[3] * c[5].zw + t0;
;             }
;             ybb[t * 32] = dy + da * bk.x + v0 * bk.y;
;         }
	v_pk_mul_f32 v[122:123], v[38:39], v[42:43]
	v_pk_mul_f32 v[124:125], v[38:39], v[50:51]
	v_pk_fma_f32 v[122:123], v[36:37], v[40:41], v[122:123]
	v_pk_fma_f32 v[124:125], v[36:37], v[48:49], v[124:125]
	v_pk_fma_f32 v[122:123], v[32:33], v[44:45], v[122:123]
	v_pk_fma_f32 v[124:125], v[32:33], v[52:53], v[124:125]
	v_pk_fma_f32 v[122:123], v[34:35], v[46:47], v[122:123]
	v_pk_fma_f32 v[124:125], v[34:35], v[54:55], v[124:125]
	v_pk_mul_f32 v[126:127], v[72:73], v[94:95] op_sel_hi:[1,0]
	v_add_f32_e32 v166, v122, v123
	v_add_f32_e32 v168, v124, v125
	v_pk_mul_f32 v[128:129], v[74:75], v[94:95] op_sel_hi:[1,0]
	v_pk_mul_f32 v[130:131], v[76:77], v[94:95] op_sel_hi:[1,0]
	v_add_f32_dpp v166, v166, v166 quad_perm:[1,0,3,2] row_mask:0xf bank_mask:0xf bound_ctrl:1
	v_add_f32_dpp v168, v168, v168 quad_perm:[1,0,3,2] row_mask:0xf bank_mask:0xf bound_ctrl:1
	v_pk_mul_f32 v[132:133], v[78:79], v[94:95] op_sel_hi:[1,0]
	v_pk_fma_f32 v[126:127], v[36:37], v[56:57], v[126:127]
	v_add_f32_dpp v166, v166, v166 quad_perm:[2,3,0,1] row_mask:0xf bank_mask:0xf bound_ctrl:1
	v_add_f32_dpp v168, v168, v168 quad_perm:[2,3,0,1] row_mask:0xf bank_mask:0xf bound_ctrl:1
	v_pk_fma_f32 v[128:129], v[38:39], v[58:59], v[128:129]
	v_pk_fma_f32 v[130:131], v[32:33], v[60:61], v[130:131]
	v_add_f32_dpp v166, v166, v166 row_half_mirror row_mask:0xf bank_mask:0xf bound_ctrl:1
	v_add_f32_dpp v168, v168, v168 row_half_mirror row_mask:0xf bank_mask:0xf bound_ctrl:1
	v_pk_fma_f32 v[132:133], v[34:35], v[62:63], v[132:133]
	v_fma_f32 v136, v166, v108, v168
	v_pk_fma_f32 v[36:37], v[64:65], v[166:167], v[126:127] op_sel_hi:[1,0,1]
	v_pk_fma_f32 v[38:39], v[66:67], v[166:167], v[128:129] op_sel_hi:[1,0,1]
	v_pk_fma_f32 v[32:33], v[68:69], v[166:167], v[130:131] op_sel_hi:[1,0,1]
	v_pk_fma_f32 v[34:35], v[70:71], v[166:167], v[132:133] op_sel_hi:[1,0,1]
	v_fma_f32 v136, v94, v109, v136
	ds_write_b32 v95, v136 offset:768
	ds_read_b128 v[40:43], v120 offset:10240
	ds_read_b128 v[44:47], v120 offset:10256
	ds_read_b128 v[48:51], v120 offset:10496
	ds_read_b128 v[52:55], v120 offset:10512
	ds_read_b128 v[56:59], v120 offset:10752
	ds_read_b128 v[60:63], v120 offset:10768
	ds_read_b128 v[64:67], v120 offset:11008
	ds_read_b128 v[68:71], v120 offset:11024
	ds_read_b128 v[72:75], v120 offset:11264
	ds_read_b128 v[76:79], v120 offset:11280
	ds_read_b32 v94, v96 offset:22528
	ds_read_b64 v[108:109], v121 offset:24704
	s_waitcnt lgkmcnt(12)
	v_pk_mul_f32 v[122:123], v[38:39], v[192:193]
	v_pk_mul_f32 v[124:125], v[38:39], v[200:201]
	v_pk_fma_f32 v[122:123], v[36:37], v[190:191], v[122:123]
	v_pk_fma_f32 v[124:125], v[36:37], v[198:199], v[124:125]
	v_pk_fma_f32 v[122:123], v[32:33], v[194:195], v[122:123]
	v_pk_fma_f32 v[124:125], v[32:33], v[202:203], v[124:125]
	v_pk_fma_f32 v[122:123], v[34:35], v[196:197], v[122:123]
	v_pk_fma_f32 v[124:125], v[34:35], v[204:205], v[124:125]
	v_pk_mul_f32 v[126:127], v[222:223], v[230:231] op_sel_hi:[1,0]
	v_add_f32_e32 v166, v122, v123
	v_add_f32_e32 v168, v124, v125
	v_pk_mul_f32 v[128:129], v[224:225], v[230:231] op_sel_hi:[1,0]
	v_pk_mul_f32 v[130:131], v[226:227], v[230:231] op_sel_hi:[1,0]
	v_add_f32_dpp v166, v166, v166 quad_perm:[1,0,3,2] row_mask:0xf bank_mask:0xf bound_ctrl:1
	v_add_f32_dpp v168, v168, v168 quad_perm:[1,0,3,2] row_mask:0xf bank_mask:0xf bound_ctrl:1
	v_pk_mul_f32 v[132:133], v[228:229], v[230:231] op_sel_hi:[1,0]
	v_pk_fma_f32 v[126:127], v[36:37], v[206:207], v[126:127]
	v_add_f32_dpp v166, v166, v166 quad_perm:[2,3,0,1] row_mask:0xf bank_mask:0xf bound_ctrl:1
	v_add_f32_dpp v168, v168, v168 quad_perm:[2,3,0,1] row_mask:0xf bank_mask:0xf bound_ctrl:1
	v_pk_fma_f32 v[128:129], v[38:39], v[208:209], v[128:129]
	v_pk_fma_f32 v[130:131], v[32:33], v[210:211], v[130:131]
	v_add_f32_dpp v166, v166, v166 row_half_mirror row_mask:0xf bank_mask:0xf bound_ctrl:1
	v_add_f32_dpp v168, v168, v168 row_half_mirror row_mask:0xf bank_mask:0xf bound_ctrl:1
	v_pk_fma_f32 v[132:133], v[34:35], v[212:213], v[132:133]
	v_fma_f32 v136, v166, v232, v168
	v_pk_fma_f32 v[36:37], v[214:215], v[166:167], v[126:127] op_sel_hi:[1,0,1]
	v_pk_fma_f32 v[38:39], v[216:217], v[166:167], v[128:129] op_sel_hi:[1,0,1]
	v_pk_fma_f32 v[32:33], v[218:219], v[166:167], v[130:131] op_sel_hi:[1,0,1]
	v_pk_fma_f32 v[34:35], v[220:221], v[166:167], v[132:133] op_sel_hi:[1,0,1]
	v_fma_f32 v136, v230, v233, v136
	ds_write_b32 v95, v136 offset:896
	ds_read_b128 v[190:193], v120 offset:11520
	ds_read_b128 v[194:197], v120 offset:11536
	ds_read_b128 v[198:201], v120 offset:11776
	ds_read_b128 v[202:205], v120 offset:11792
	ds_read_b128 v[206:209], v120 offset:12032
	ds_read_b128 v[210:213], v120 offset:12048
	ds_read_b128 v[214:217], v120 offset:12288
	ds_read_b128 v[218:221], v120 offset:12304
	ds_read_b128 v[222:225], v120 offset:12544
	ds_read_b128 v[226:229], v120 offset:12560
	ds_read_b32 v230, v96 offset:22784
	ds_read_b64 v[232:233], v121 offset:24720
	s_waitcnt lgkmcnt(12)
; #define SC_LOAD(t) { _Pragma("unroll") for (int q = 0; q < 5; ++q) { n[2 * q] = *(const LAS f32x4*)(opb + (t) * 320 + q * 64); n[2 * q + 1] = *(const LAS f32x4*)(opb + (t) * 320 + q * 64 + 4); } \
;                      nv = vvb[(t) * 64]; nbk = *(const LAS f32x2*)(scb + (t) * 4); }
; DI void scan_item(const __attribute__((address_space(4))) Args& a, LAS unsigned char* lds, int ws_, bool is_prompt, int seq, int h, int half, bool dry = false) {
;     ...
;         SC_LOAD(0)
; #pragma unroll 4
;         for (int t = 0; t < SC_CH; ++t) {
;             f32x4 c[10];
; #pragma unroll
;             for (int q = 0; q < 10; ++q) c[q] = n[q];
;             const float v0 = nv; const f32x2 bk = nbk;
;             SC_LOAD(t + 1)
;             __builtin_amdgcn_sched_barrier(0);
;             f32x2 aA = sp[0] * c[0].xy, aY = sp[0] * c[2].xy;
;             aA = sp[1] * c[0].zw + aA; aY = sp[1] * c[2].zw + aY;
;             aA = sp[2] * c[1].xy + aA; aY = sp[2] * c[3].xy + aY;
;             aA = sp[3] * c[1].zw + aA; aY = sp[3] * c[3].zw + aY;
;             float da = aA.x + aA.y, dy = aY.x + aY.y;
;             asm("s_nop 1\n\t"
;                 "v_add_f32_dpp %0, %0, %0 quad_perm:[1,0,3,2] row_mask:0xf bank_mask:0xf bound_ctrl:1\n\t"
;                 "v_add_f32_dpp %1, %1, %1 quad_perm:[1,0,3,2] row_mask:0xf bank_mask:0xf bound_ctrl:1\n\t"
;                 "s_nop 0\n\t"
;                 "v_add_f32_dpp %0, %0, %0 quad_perm:[2,3,0,1] row_mask:0xf bank_mask:0xf bound_ctrl:1\n\t"
;                 "v_add_f32_dpp %1, %1, %1 quad_perm:[2,3,0,1] row_mask:0xf bank_mask:0xf bound_ctrl:1\n\t"
;                 "s_nop 0\n\t"
;                 "v_add_f32_dpp %0, %0, %0 row_half_mirror row_mask:0xf bank_mask:0xf bound_ctrl:1\n\t"
;                 "v_add_f32_dpp %1, %1, %1 row_half_mirror row_mask:0xf bank_mask:0xf bound_ctrl:1"
;                 : "+v"(da), "+v"(dy));
;             {
;                 f32x2 t0;
;                 t0 = c[8].xy * v0; t0 = c[6].xy * da + t0; sp[0] = sp[0] * c[4].xy + t0;
;                 t0 = c[8].zw * v0; t0 = c[6].zw * da + t0; sp[1] = sp[1] * c[4].zw + t0;
;                 t0 = c[9].xy * v0; t0 = c[7].xy * da + t0; sp[2] = sp[2] * c[5].xy + t0;
;                 t0 = c[9].zw * v0; t0 = c[7].zw * da + t0; sp[3] = sp[3] * c[5].zw + t0;
;             }
;             ybb[t * 32] = dy + da * bk.x + v0 * bk.y;
;         }
	v_pk_mul_f32 v[122:123], v[38:39], v[42:43]
	v_pk_mul_f32 v[124:125], v[38:39], v[50:51]
	v_pk_fma_f32 v[122:123], v[36:37], v[40:41], v[122:123]
	v_pk_fma_f32 v[124:125], v[36:37], v[48:49], v[124:125]
	v_pk_fma_f32 v[122:123], v[32:33], v[44:45], v[122:123]
	v_pk_fma_f32 v[124:125], v[32:33], v[52:53], v[124:125]
	v_pk_fma_f32 v[122:123], v[34:35], v[46:47], v[122:123]
	v_pk_fma_f32 v[124:125], v[34:35], v[54:55], v[124:125]
	v_pk_mul_f32 v[126:127], v[72:73], v[94:95] op_sel_hi:[1,0]
	v_add_f32_e32 v166, v122, v123
	v_add_f32_e32 v168, v124, v125
	v_pk_mul_f32 v[128:129], v[74:75], v[94:95] op_sel_hi:[1,0]
	v_pk_mul_f32 v[130:131], v[76:77], v[94:95] op_sel_hi:[1,0]
	v_add_f32_dpp v166, v166, v166 quad_perm:[1,0,3,2] row_mask:0xf bank_mask:0xf bound_ctrl:1
	v_add_f32_dpp v168, v168, v168 quad_perm:[1,0,3,2] row_mask:0xf bank_mask:0xf bound_ctrl:1
	v_pk_mul_f32 v[132:133], v[78:79], v[94:95] op_sel_hi:[1,0]
	v_pk_fma_f32 v[126:127], v[36:37], v[56:57], v[126:127]
	v_add_f32_dpp v166, v166, v166 quad_perm:[2,3,0,1] row_mask:0xf bank_mask:0xf bound_ctrl:1
	v_add_f32_dpp v168, v168, v168 quad_perm:[2,3,0,1] row_mask:0xf bank_mask:0xf bound_ctrl:1
	v_pk_fma_f32 v[128:129], v[38:39], v[58:59], v[128:129]
	v_pk_fma_f32 v[130:131], v[32:33], v[60:61], v[130:131]
	v_add_f32_dpp v166, v166, v166 row_half_mirror row_mask:0xf bank_mask:0xf bound_ctrl:1
	v_add_f32_dpp v168, v168, v168 row_half_mirror row_mask:0xf bank_mask:0xf bound_ctrl:1
	v_pk_fma_f32 v[132:133], v[34:35], v[62:63], v[132:133]
	v_fma_f32 v136, v166, v108, v168
	v_pk_fma_f32 v[36:37], v[64:65], v[166:167], v[126:127] op_sel_hi:[1,0,1]
	v_pk_fma_f32 v[38:39], v[66:67], v[166:167], v[128:129] op_sel_hi:[1,0,1]
	v_pk_fma_f32 v[32:33], v[68:69], v[166:167], v[130:131] op_sel_hi:[1,0,1]
	v_pk_fma_f32 v[34:35], v[70:71], v[166:167], v[132:133] op_sel_hi:[1,0,1]
	v_fma_f32 v136, v94, v109, v136
	ds_write_b32 v95, v136 offset:1024
	ds_read_b128 v[40:43], v120 offset:12800
	ds_read_b128 v[44:47], v120 offset:12816
	ds_read_b128 v[48:51], v120 offset:13056
	ds_read_b128 v[52:55], v120 offset:13072
	ds_read_b128 v[56:59], v120 offset:13312
	ds_read_b128 v[60:63], v120 offset:13328
	ds_read_b128 v[64:67], v120 offset:13568
	ds_read_b128 v[68:71], v120 offset:13584
	ds_read_b128 v[72:75], v120 offset:13824
	ds_read_b128 v[76:79], v120 offset:13840
	ds_read_b32 v94, v96 offset:23040
	ds_read_b64 v[108:109], v121 offset:24736
	s_waitcnt lgkmcnt(12)
	v_pk_mul_f32 v[122:123], v[38:39], v[192:193]
	v_pk_mul_f32 v[124:125], v[38:39], v[200:201]
	v_pk_fma_f32 v[122:123], v[36:37], v[190:191], v[122:123]
	v_pk_fma_f32 v[124:125], v[36:37], v[198:199], v[124:125]
	v_pk_fma_f32 v[122:123], v[32:33], v[194:195], v[122:123]
	v_pk_fma_f32 v[124:125], v[32:33], v[202:203], v[124:125]
	v_pk_fma_f32 v[122:123], v[34:35], v[196:197], v[122:123]
	v_pk_fma_f32 v[124:125], v[34:35], v[204:205], v[124:125]
	v_pk_mul_f32 v[126:127], v[222:223], v[230:231] op_sel_hi:[1,0]
	v_add_f32_e32 v166, v122, v123
	v_add_f32_e32 v168, v124, v125
	v_pk_mul_f32 v[128:129], v[224:225], v[230:231] op_sel_hi:[1,0]
	v_pk_mul_f32 v[130:131], v[226:227], v[230:231] op_sel_hi:[1,0]
	v_add_f32_dpp v166, v166, v166 quad_perm:[1,0,3,2] row_mask:0xf bank_mask:0xf bound_ctrl:1
	v_add_f32_dpp v168, v168, v168 quad_perm:[1,0,3,2] row_mask:0xf bank_mask:0xf bound_ctrl:1
	v_pk_mul_f32 v[132:133], v[228:229], v[230:231] op_sel_hi:[1,0]
	v_pk_fma_f32 v[126:127], v[36:37], v[206:207], v[126:127]
	v_add_f32_dpp v166, v166, v166 quad_perm:[2,3,0,1] row_mask:0xf bank_mask:0xf bound_ctrl:1
	v_add_f32_dpp v168, v168, v168 quad_perm:[2,3,0,1] row_mask:0xf bank_mask:0xf bound_ctrl:1
	v_pk_fma_f32 v[128:129], v[38:39], v[208:209], v[128:129]
	v_pk_fma_f32 v[130:131], v[32:33], v[210:211], v[130:131]
	v_add_f32_dpp v166, v166, v166 row_half_mirror row_mask:0xf bank_mask:0xf bound_ctrl:1
	v_add_f32_dpp v168, v168, v168 row_half_mirror row_mask:0xf bank_mask:0xf bound_ctrl:1
	v_pk_fma_f32 v[132:133], v[34:35], v[212:213], v[132:133]
	v_fma_f32 v136, v166, v232, v168
	v_pk_fma_f32 v[36:37], v[214:215], v[166:167], v[126:127] op_sel_hi:[1,0,1]
	v_pk_fma_f32 v[38:39], v[216:217], v[166:167], v[128:129] op_sel_hi:[1,0,1]
	v_pk_fma_f32 v[32:33], v[218:219], v[166:167], v[130:131] op_sel_hi:[1,0,1]
	v_pk_fma_f32 v[34:35], v[220:221], v[166:167], v[132:133] op_sel_hi:[1,0,1]
	v_fma_f32 v136, v230, v233, v136
	ds_write_b32 v95, v136 offset:1152
	ds_read_b128 v[190:193], v120 offset:14080
	ds_read_b128 v[194:197], v120 offset:14096
	ds_read_b128 v[198:201], v120 offset:14336
	ds_read_b128 v[202:205], v120 offset:14352
	ds_read_b128 v[206:209], v120 offset:14592
	ds_read_b128 v[210:213], v120 offset:14608
	ds_read_b128 v[214:217], v120 offset:14848
	ds_read_b128 v[218:221], v120 offset:14864
	ds_read_b128 v[222:225], v120 offset:15104
	ds_read_b128 v[226:229], v120 offset:15120
	ds_read_b32 v230, v96 offset:23296
	ds_read_b64 v[232:233], v121 offset:24752
	s_waitcnt lgkmcnt(12)
; #define SC_LOAD(t) { _Pragma("unroll") for (int q = 0; q < 5; ++q) { n[2 * q] = *(const LAS f32x4*)(opb + (t) * 320 + q * 64); n[2 * q + 1] = *(const LAS f32x4*)(opb + (t) * 320 + q * 64 + 4); } \
;                      nv = vvb[(t) * 64]; nbk = *(const LAS f32x2*)(scb + (t) * 4); }
; DI void scan_item(const __attribute__((address_space(4))) Args& a, LAS unsigned char* lds, int ws_, bool is_prompt, int seq, int h, int half, bool dry = false) {
;     ...
;         SC_LOAD(0)
; #pragma unroll 4
;         for (int t = 0; t < SC_CH; ++t) {
;             f32x4 c[10];
; #pragma unroll
;             for (int q = 0; q < 10; ++q) c[q] = n[q];
;             const float v0 = nv; const f32x2 bk = nbk;
;             SC_LOAD(t + 1)
;             __builtin_amdgcn_sched_barrier(0);
;             f32x2 aA = sp[0] * c[0].xy, aY = sp[0] * c[2].xy;
;             aA = sp[1] * c[0].zw + aA; aY = sp[1] * c[2].zw + aY;
;             aA = sp[2] * c[1].xy + aA; aY = sp[2] * c[3].xy + aY;
;             aA = sp[3] * c[1].zw + aA; aY = sp[3] * c[3].zw + aY;
;             float da = aA.x + aA.y, dy = aY.x + aY.y;
;             asm("s_nop 1\n\t"
;                 "v_add_f32_dpp %0, %0, %0 quad_perm:[1,0,3,2] row_mask:0xf bank_mask:0xf bound_ctrl:1\n\t"
;                 "v_add_f32_dpp %1, %1, %1 quad_perm:[1,0,3,2] row_mask:0xf bank_mask:0xf bound_ctrl:1\n\t"
;                 "s_nop 0\n\t"
;                 "v_add_f32_dpp %0, %0, %0 quad_perm:[2,3,0,1] row_mask:0xf bank_mask:0xf bound_ctrl:1\n\t"
;                 "v_add_f32_dpp %1, %1, %1 quad_perm:[2,3,0,1] row_mask:0xf bank_mask:0xf bound_ctrl:1\n\t"
;                 "s_nop 0\n\t"
;                 "v_add_f32_dpp %0, %0, %0 row_half_mirror row_mask:0xf bank_mask:0xf bound_ctrl:1\n\t"
;                 "v_add_f32_dpp %1, %1, %1 row_half_mirror row_mask:0xf bank_mask:0xf bound_ctrl:1"
;                 : "+v"(da), "+v"(dy));
;             {
;                 f32x2 t0;
;                 t0 = c[8].xy * v0; t0 = c[6].xy * da + t0; sp[0] = sp[0] * c[4].xy + t0;
;                 t0 = c[8].zw * v0; t0 = c[6].zw * da + t0; sp[1] = sp[1] * c[4].zw + t0;
;                 t0 = c[9].xy * v0; t0 = c[7].xy * da + t0; sp[2] = sp[2] * c[5].xy + t0;
;                 t0 = c[9].zw * v0; t0 = c[7].zw * da + t0; sp[3] = sp[3] * c[5].zw + t0;
;             }
;             ybb[t * 32] = dy + da * bk.x + v0 * bk.y;
;         }
	v_pk_mul_f32 v[122:123], v[38:39], v[42:43]
	v_pk_mul_f32 v[124:125], v[38:39], v[50:51]
	v_pk_fma_f32 v[122:123], v[36:37], v[40:41], v[122:123]
	v_pk_fma_f32 v[124:125], v[36:37], v[48:49], v[124:125]
	v_pk_fma_f32 v[122:123], v[32:33], v[44:45], v[122:123]
	v_pk_fma_f32 v[124:125], v[32:33], v[52:53], v[124:125]
	v_pk_fma_f32 v[122:123], v[34:35], v[46:47], v[122:123]
	v_pk_fma_f32 v[124:125], v[34:35], v[54:55], v[124:125]
	v_pk_mul_f32 v[126:127], v[72:73], v[94:95] op_sel_hi:[1,0]
	v_add_f32_e32 v166, v122, v123
	v_add_f32_e32 v168, v124, v125
	v_pk_mul_f32 v[128:129], v[74:75], v[94:95] op_sel_hi:[1,0]
	v_pk_mul_f32 v[130:131], v[76:77], v[94:95] op_sel_hi:[1,0]
	v_add_f32_dpp v166, v166, v166 quad_perm:[1,0,3,2] row_mask:0xf bank_mask:0xf bound_ctrl:1
	v_add_f32_dpp v168, v168, v168 quad_perm:[1,0,3,2] row_mask:0xf bank_mask:0xf bound_ctrl:1
	v_pk_mul_f32 v[132:133], v[78:79], v[94:95] op_sel_hi:[1,0]
	v_pk_fma_f32 v[126:127], v[36:37], v[56:57], v[126:127]
	v_add_f32_dpp v166, v166, v166 quad_perm:[2,3,0,1] row_mask:0xf bank_mask:0xf bound_ctrl:1
	v_add_f32_dpp v168, v168, v168 quad_perm:[2,3,0,1] row_mask:0xf bank_mask:0xf bound_ctrl:1
	v_pk_fma_f32 v[128:129], v[38:39], v[58:59], v[128:129]
	v_pk_fma_f32 v[130:131], v[32:33], v[60:61], v[130:131]
	v_add_f32_dpp v166, v166, v166 row_half_mirror row_mask:0xf bank_mask:0xf bound_ctrl:1
	v_add_f32_dpp v168, v168, v168 row_half_mirror row_mask:0xf bank_mask:0xf bound_ctrl:1
	v_pk_fma_f32 v[132:133], v[34:35], v[62:63], v[132:133]
	v_fma_f32 v136, v166, v108, v168
	v_pk_fma_f32 v[36:37], v[64:65], v[166:167], v[126:127] op_sel_hi:[1,0,1]
	v_pk_fma_f32 v[38:39], v[66:67], v[166:167], v[128:129] op_sel_hi:[1,0,1]
	v_pk_fma_f32 v[32:33], v[68:69], v[166:167], v[130:131] op_sel_hi:[1,0,1]
	v_pk_fma_f32 v[34:35], v[70:71], v[166:167], v[132:133] op_sel_hi:[1,0,1]
	v_fma_f32 v136, v94, v109, v136
	ds_write_b32 v95, v136 offset:1280
	ds_read_b128 v[40:43], v120 offset:15360
	ds_read_b128 v[44:47], v120 offset:15376
	ds_read_b128 v[48:51], v120 offset:15616
	ds_read_b128 v[52:55], v120 offset:15632
	ds_read_b128 v[56:59], v120 offset:15872
	ds_read_b128 v[60:63], v120 offset:15888
	ds_read_b128 v[64:67], v120 offset:16128
	ds_read_b128 v[68:71], v120 offset:16144
	ds_read_b128 v[72:75], v120 offset:16384
	ds_read_b128 v[76:79], v120 offset:16400
	ds_read_b32 v94, v96 offset:23552
	ds_read_b64 v[108:109], v121 offset:24768
	s_waitcnt lgkmcnt(12)
	v_pk_mul_f32 v[122:123], v[38:39], v[192:193]
	v_pk_mul_f32 v[124:125], v[38:39], v[200:201]
	v_pk_fma_f32 v[122:123], v[36:37], v[190:191], v[122:123]
	v_pk_fma_f32 v[124:125], v[36:37], v[198:199], v[124:125]
	v_pk_fma_f32 v[122:123], v[32:33], v[194:195], v[122:123]
	v_pk_fma_f32 v[124:125], v[32:33], v[202:203], v[124:125]
	v_pk_fma_f32 v[122:123], v[34:35], v[196:197], v[122:123]
	v_pk_fma_f32 v[124:125], v[34:35], v[204:205], v[124:125]
	v_pk_mul_f32 v[126:127], v[222:223], v[230:231] op_sel_hi:[1,0]
	v_add_f32_e32 v166, v122, v123
	v_add_f32_e32 v168, v124, v125
	v_pk_mul_f32 v[128:129], v[224:225], v[230:231] op_sel_hi:[1,0]
	v_pk_mul_f32 v[130:131], v[226:227], v[230:231] op_sel_hi:[1,0]
	v_add_f32_dpp v166, v166, v166 quad_perm:[1,0,3,2] row_mask:0xf bank_mask:0xf bound_ctrl:1
	v_add_f32_dpp v168, v168, v168 quad_perm:[1,0,3,2] row_mask:0xf bank_mask:0xf bound_ctrl:1
	v_pk_mul_f32 v[132:133], v[228:229], v[230:231] op_sel_hi:[1,0]
	v_pk_fma_f32 v[126:127], v[36:37], v[206:207], v[126:127]
	v_add_f32_dpp v166, v166, v166 quad_perm:[2,3,0,1] row_mask:0xf bank_mask:0xf bound_ctrl:1
	v_add_f32_dpp v168, v168, v168 quad_perm:[2,3,0,1] row_mask:0xf bank_mask:0xf bound_ctrl:1
	v_pk_fma_f32 v[128:129], v[38:39], v[208:209], v[128:129]
	v_pk_fma_f32 v[130:131], v[32:33], v[210:211], v[130:131]
	v_add_f32_dpp v166, v166, v166 row_half_mirror row_mask:0xf bank_mask:0xf bound_ctrl:1
	v_add_f32_dpp v168, v168, v168 row_half_mirror row_mask:0xf bank_mask:0xf bound_ctrl:1
	v_pk_fma_f32 v[132:133], v[34:35], v[212:213], v[132:133]
	v_fma_f32 v136, v166, v232, v168
	v_pk_fma_f32 v[36:37], v[214:215], v[166:167], v[126:127] op_sel_hi:[1,0,1]
	v_pk_fma_f32 v[38:39], v[216:217], v[166:167], v[128:129] op_sel_hi:[1,0,1]
	v_pk_fma_f32 v[32:33], v[218:219], v[166:167], v[130:131] op_sel_hi:[1,0,1]
	v_pk_fma_f32 v[34:35], v[220:221], v[166:167], v[132:133] op_sel_hi:[1,0,1]
	v_fma_f32 v136, v230, v233, v136
	ds_write_b32 v95, v136 offset:1408
	ds_read_b128 v[190:193], v120 offset:16640
	ds_read_b128 v[194:197], v120 offset:16656
	ds_read_b128 v[198:201], v120 offset:16896
	ds_read_b128 v[202:205], v120 offset:16912
	ds_read_b128 v[206:209], v120 offset:17152
	ds_read_b128 v[210:213], v120 offset:17168
	ds_read_b128 v[214:217], v120 offset:17408
	ds_read_b128 v[218:221], v120 offset:17424
	ds_read_b128 v[222:225], v120 offset:17664
	ds_read_b128 v[226:229], v120 offset:17680
	ds_read_b32 v230, v96 offset:23808
	ds_read_b64 v[232:233], v121 offset:24784
	s_waitcnt lgkmcnt(12)
; #define SC_LOAD(t) { _Pragma("unroll") for (int q = 0; q < 5; ++q) { n[2 * q] = *(const LAS f32x4*)(opb + (t) * 320 + q * 64); n[2 * q + 1] = *(const LAS f32x4*)(opb + (t) * 320 + q * 64 + 4); } \
;                      nv = vvb[(t) * 64]; nbk = *(const LAS f32x2*)(scb + (t) * 4); }
; DI void scan_item(const __attribute__((address_space(4))) Args& a, LAS unsigned char* lds, int ws_, bool is_prompt, int seq, int h, int half, bool dry = false) {
;     ...
;         SC_LOAD(0)
; #pragma unroll 4
;         for (int t = 0; t < SC_CH; ++t) {
;             f32x4 c[10];
; #pragma unroll
;             for (int q = 0; q < 10; ++q) c[q] = n[q];
;             const float v0 = nv; const f32x2 bk = nbk;
;             SC_LOAD(t + 1)
;             __builtin_amdgcn_sched_barrier(0);
;             f32x2 aA = sp[0] * c[0].xy, aY = sp[0] * c[2].xy;
;             aA = sp[1] * c[0].zw + aA; aY = sp[1] * c[2].zw + aY;
;             aA = sp[2] * c[1].xy + aA; aY = sp[2] * c[3].xy + aY;
;             aA = sp[3] * c[1].zw + aA; aY = sp[3] * c[3].zw + aY;
;             float da = aA.x + aA.y, dy = aY.x + aY.y;
;             asm("s_nop 1\n\t"
;                 "v_add_f32_dpp %0, %0, %0 quad_perm:[1,0,3,2] row_mask:0xf bank_mask:0xf bound_ctrl:1\n\t"
;                 "v_add_f32_dpp %1, %1, %1 quad_perm:[1,0,3,2] row_mask:0xf bank_mask:0xf bound_ctrl:1\n\t"
;                 "s_nop 0\n\t"
;                 "v_add_f32_dpp %0, %0, %0 quad_perm:[2,3,0,1] row_mask:0xf bank_mask:0xf bound_ctrl:1\n\t"
;                 "v_add_f32_dpp %1, %1, %1 quad_perm:[2,3,0,1] row_mask:0xf bank_mask:0xf bound_ctrl:1\n\t"
;                 "s_nop 0\n\t"
;                 "v_add_f32_dpp %0, %0, %0 row_half_mirror row_mask:0xf bank_mask:0xf bound_ctrl:1\n\t"
;                 "v_add_f32_dpp %1, %1, %1 row_half_mirror row_mask:0xf bank_mask:0xf bound_ctrl:1"
;                 : "+v"(da), "+v"(dy));
;             {
;                 f32x2 t0;
;                 t0 = c[8].xy * v0; t0 = c[6].xy * da + t0; sp[0] = sp[0] * c[4].xy + t0;
;                 t0 = c[8].zw * v0; t0 = c[6].zw * da + t0; sp[1] = sp[1] * c[4].zw + t0;
;                 t0 = c[9].xy * v0; t0 = c[7].xy * da + t0; sp[2] = sp[2] * c[5].xy + t0;
;                 t0 = c[9].zw * v0; t0 = c[7].zw * da + t0; sp[3] = sp[3] * c[5].zw + t0;
;             }
;             ybb[t * 32] = dy + da * bk.x + v0 * bk.y;
;         }
	v_pk_mul_f32 v[122:123], v[38:39], v[42:43]
	v_pk_mul_f32 v[124:125], v[38:39], v[50:51]
	v_pk_fma_f32 v[122:123], v[36:37], v[40:41], v[122:123]
	v_pk_fma_f32 v[124:125], v[36:37], v[48:49], v[124:125]
	v_pk_fma_f32 v[122:123], v[32:33], v[44:45], v[122:123]
	v_pk_fma_f32 v[124:125], v[32:33], v[52:53], v[124:125]
	v_pk_fma_f32 v[122:123], v[34:35], v[46:47], v[122:123]
	v_pk_fma_f32 v[124:125], v[34:35], v[54:55], v[124:125]
	v_pk_mul_f32 v[126:127], v[72:73], v[94:95] op_sel_hi:[1,0]
	v_add_f32_e32 v166, v122, v123
	v_add_f32_e32 v168, v124, v125
	v_pk_mul_f32 v[128:129], v[74:75], v[94:95] op_sel_hi:[1,0]
	v_pk_mul_f32 v[130:131], v[76:77], v[94:95] op_sel_hi:[1,0]
	v_add_f32_dpp v166, v166, v166 quad_perm:[1,0,3,2] row_mask:0xf bank_mask:0xf bound_ctrl:1
	v_add_f32_dpp v168, v168, v168 quad_perm:[1,0,3,2] row_mask:0xf bank_mask:0xf bound_ctrl:1
	v_pk_mul_f32 v[132:133], v[78:79], v[94:95] op_sel_hi:[1,0]
	v_pk_fma_f32 v[126:127], v[36:37], v[56:57], v[126:127]
	v_add_f32_dpp v166, v166, v166 quad_perm:[2,3,0,1] row_mask:0xf bank_mask:0xf bound_ctrl:1
	v_add_f32_dpp v168, v168, v168 quad_perm:[2,3,0,1] row_mask:0xf bank_mask:0xf bound_ctrl:1
	v_pk_fma_f32 v[128:129], v[38:39], v[58:59], v[128:129]
	v_pk_fma_f32 v[130:131], v[32:33], v[60:61], v[130:131]
	v_add_f32_dpp v166, v166, v166 row_half_mirror row_mask:0xf bank_mask:0xf bound_ctrl:1
	v_add_f32_dpp v168, v168, v168 row_half_mirror row_mask:0xf bank_mask:0xf bound_ctrl:1
	v_pk_fma_f32 v[132:133], v[34:35], v[62:63], v[132:133]
	v_fma_f32 v136, v166, v108, v168
	v_pk_fma_f32 v[36:37], v[64:65], v[166:167], v[126:127] op_sel_hi:[1,0,1]
	v_pk_fma_f32 v[38:39], v[66:67], v[166:167], v[128:129] op_sel_hi:[1,0,1]
	v_pk_fma_f32 v[32:33], v[68:69], v[166:167], v[130:131] op_sel_hi:[1,0,1]
	v_pk_fma_f32 v[34:35], v[70:71], v[166:167], v[132:133] op_sel_hi:[1,0,1]
	v_fma_f32 v136, v94, v109, v136
	ds_write_b32 v95, v136 offset:1536
	ds_read_b128 v[40:43], v120 offset:17920
	ds_read_b128 v[44:47], v120 offset:17936
	ds_read_b128 v[48:51], v120 offset:18176
	ds_read_b128 v[52:55], v120 offset:18192
	ds_read_b128 v[56:59], v120 offset:18432
	ds_read_b128 v[60:63], v120 offset:18448
	ds_read_b128 v[64:67], v120 offset:18688
	ds_read_b128 v[68:71], v120 offset:18704
	ds_read_b128 v[72:75], v120 offset:18944
	ds_read_b128 v[76:79], v120 offset:18960
	ds_read_b32 v94, v96 offset:24064
	ds_read_b64 v[108:109], v121 offset:24800
	s_waitcnt lgkmcnt(12)
	v_pk_mul_f32 v[122:123], v[38:39], v[192:193]
	v_pk_mul_f32 v[124:125], v[38:39], v[200:201]
	v_pk_fma_f32 v[122:123], v[36:37], v[190:191], v[122:123]
	v_pk_fma_f32 v[124:125], v[36:37], v[198:199], v[124:125]
	v_pk_fma_f32 v[122:123], v[32:33], v[194:195], v[122:123]
	v_pk_fma_f32 v[124:125], v[32:33], v[202:203], v[124:125]
	v_pk_fma_f32 v[122:123], v[34:35], v[196:197], v[122:123]
	v_pk_fma_f32 v[124:125], v[34:35], v[204:205], v[124:125]
	v_pk_mul_f32 v[126:127], v[222:223], v[230:231] op_sel_hi:[1,0]
	v_add_f32_e32 v166, v122, v123
	v_add_f32_e32 v168, v124, v125
	v_pk_mul_f32 v[128:129], v[224:225], v[230:231] op_sel_hi:[1,0]
	v_pk_mul_f32 v[130:131], v[226:227], v[230:231] op_sel_hi:[1,0]
	v_add_f32_dpp v166, v166, v166 quad_perm:[1,0,3,2] row_mask:0xf bank_mask:0xf bound_ctrl:1
	v_add_f32_dpp v168, v168, v168 quad_perm:[1,0,3,2] row_mask:0xf bank_mask:0xf bound_ctrl:1
	v_pk_mul_f32 v[132:133], v[228:229], v[230:231] op_sel_hi:[1,0]
	v_pk_fma_f32 v[126:127], v[36:37], v[206:207], v[126:127]
	v_add_f32_dpp v166, v166, v166 quad_perm:[2,3,0,1] row_mask:0xf bank_mask:0xf bound_ctrl:1
	v_add_f32_dpp v168, v168, v168 quad_perm:[2,3,0,1] row_mask:0xf bank_mask:0xf bound_ctrl:1
	v_pk_fma_f32 v[128:129], v[38:39], v[208:209], v[128:129]
	v_pk_fma_f32 v[130:131], v[32:33], v[210:211], v[130:131]
	v_add_f32_dpp v166, v166, v166 row_half_mirror row_mask:0xf bank_mask:0xf bound_ctrl:1
	v_add_f32_dpp v168, v168, v168 row_half_mirror row_mask:0xf bank_mask:0xf bound_ctrl:1
	v_pk_fma_f32 v[132:133], v[34:35], v[212:213], v[132:133]
	v_fma_f32 v136, v166, v232, v168
	v_pk_fma_f32 v[36:37], v[214:215], v[166:167], v[126:127] op_sel_hi:[1,0,1]
	v_pk_fma_f32 v[38:39], v[216:217], v[166:167], v[128:129] op_sel_hi:[1,0,1]
	v_pk_fma_f32 v[32:33], v[218:219], v[166:167], v[130:131] op_sel_hi:[1,0,1]
	v_pk_fma_f32 v[34:35], v[220:221], v[166:167], v[132:133] op_sel_hi:[1,0,1]
	v_fma_f32 v136, v230, v233, v136
	ds_write_b32 v95, v136 offset:1664
	ds_read_b128 v[190:193], v120 offset:19200
	ds_read_b128 v[194:197], v120 offset:19216
	ds_read_b128 v[198:201], v120 offset:19456
	ds_read_b128 v[202:205], v120 offset:19472
	ds_read_b128 v[206:209], v120 offset:19712
	ds_read_b128 v[210:213], v120 offset:19728
	ds_read_b128 v[214:217], v120 offset:19968
	ds_read_b128 v[218:221], v120 offset:19984
	ds_read_b128 v[222:225], v120 offset:20224
	ds_read_b128 v[226:229], v120 offset:20240
	ds_read_b32 v230, v96 offset:24320
	ds_read_b64 v[232:233], v121 offset:24816
	s_waitcnt lgkmcnt(12)
; #define SC_LOAD(t) { _Pragma("unroll") for (int q = 0; q < 5; ++q) { n[2 * q] = *(const LAS f32x4*)(opb + (t) * 320 + q * 64); n[2 * q + 1] = *(const LAS f32x4*)(opb + (t) * 320 + q * 64 + 4); } \
;                      nv = vvb[(t) * 64]; nbk = *(const LAS f32x2*)(scb + (t) * 4); }
; DI void scan_item(const __attribute__((address_space(4))) Args& a, LAS unsigned char* lds, int ws_, bool is_prompt, int seq, int h, int half, bool dry = false) {
;     ...
;         SC_LOAD(0)
; #pragma unroll 4
;         for (int t = 0; t < SC_CH; ++t) {
;             f32x4 c[10];
; #pragma unroll
;             for (int q = 0; q < 10; ++q) c[q] = n[q];
;             const float v0 = nv; const f32x2 bk = nbk;
;             SC_LOAD(t + 1)
;             __builtin_amdgcn_sched_barrier(0);
;             f32x2 aA = sp[0] * c[0].xy, aY = sp[0] * c[2].xy;
;             aA = sp[1] * c[0].zw + aA; aY = sp[1] * c[2].zw + aY;
;             aA = sp[2] * c[1].xy + aA; aY = sp[2] * c[3].xy + aY;
;             aA = sp[3] * c[1].zw + aA; aY = sp[3] * c[3].zw + aY;
;             float da = aA.x + aA.y, dy = aY.x + aY.y;
;             asm("s_nop 1\n\t"
;                 "v_add_f32_dpp %0, %0, %0 quad_perm:[1,0,3,2] row_mask:0xf bank_mask:0xf bound_ctrl:1\n\t"
;                 "v_add_f32_dpp %1, %1, %1 quad_perm:[1,0,3,2] row_mask:0xf bank_mask:0xf bound_ctrl:1\n\t"
;                 "s_nop 0\n\t"
;                 "v_add_f32_dpp %0, %0, %0 quad_perm:[2,3,0,1] row_mask:0xf bank_mask:0xf bound_ctrl:1\n\t"
;                 "v_add_f32_dpp %1, %1, %1 quad_perm:[2,3,0,1] row_mask:0xf bank_mask:0xf bound_ctrl:1\n\t"
;                 "s_nop 0\n\t"
;                 "v_add_f32_dpp %0, %0, %0 row_half_mirror row_mask:0xf bank_mask:0xf bound_ctrl:1\n\t"
;                 "v_add_f32_dpp %1, %1, %1 row_half_mirror row_mask:0xf bank_mask:0xf bound_ctrl:1"
;                 : "+v"(da), "+v"(dy));
;             {
;                 f32x2 t0;
;                 t0 = c[8].xy * v0; t0 = c[6].xy * da + t0; sp[0] = sp[0] * c[4].xy + t0;
;                 t0 = c[8].zw * v0; t0 = c[6].zw * da + t0; sp[1] = sp[1] * c[4].zw + t0;
;                 t0 = c[9].xy * v0; t0 = c[7].xy * da + t0; sp[2] = sp[2] * c[5].xy + t0;
;                 t0 = c[9].zw * v0; t0 = c[7].zw * da + t0; sp[3] = sp[3] * c[5].zw + t0;
;             }
;             ybb[t * 32] = dy + da * bk.x + v0 * bk.y;
;         }
	v_pk_mul_f32 v[122:123], v[38:39], v[42:43]
	v_pk_mul_f32 v[124:125], v[38:39], v[50:51]
	v_pk_fma_f32 v[122:123], v[36:37], v[40:41], v[122:123]
	v_pk_fma_f32 v[124:125], v[36:37], v[48:49], v[124:125]
	v_pk_fma_f32 v[122:123], v[32:33], v[44:45], v[122:123]
	v_pk_fma_f32 v[124:125], v[32:33], v[52:53], v[124:125]
	v_pk_fma_f32 v[122:123], v[34:35], v[46:47], v[122:123]
	v_pk_fma_f32 v[124:125], v[34:35], v[54:55], v[124:125]
	v_pk_mul_f32 v[126:127], v[72:73], v[94:95] op_sel_hi:[1,0]
	v_add_f32_e32 v166, v122, v123
	v_add_f32_e32 v168, v124, v125
	v_pk_mul_f32 v[128:129], v[74:75], v[94:95] op_sel_hi:[1,0]
	v_pk_mul_f32 v[130:131], v[76:77], v[94:95] op_sel_hi:[1,0]
	v_add_f32_dpp v166, v166, v166 quad_perm:[1,0,3,2] row_mask:0xf bank_mask:0xf bound_ctrl:1
	v_add_f32_dpp v168, v168, v168 quad_perm:[1,0,3,2] row_mask:0xf bank_mask:0xf bound_ctrl:1
	v_pk_mul_f32 v[132:133], v[78:79], v[94:95] op_sel_hi:[1,0]
	v_pk_fma_f32 v[126:127], v[36:37], v[56:57], v[126:127]
	v_add_f32_dpp v166, v166, v166 quad_perm:[2,3,0,1] row_mask:0xf bank_mask:0xf bound_ctrl:1
	v_add_f32_dpp v168, v168, v168 quad_perm:[2,3,0,1] row_mask:0xf bank_mask:0xf bound_ctrl:1
	v_pk_fma_f32 v[128:129], v[38:39], v[58:59], v[128:129]
	v_pk_fma_f32 v[130:131], v[32:33], v[60:61], v[130:131]
	v_add_f32_dpp v166, v166, v166 row_half_mirror row_mask:0xf bank_mask:0xf bound_ctrl:1
	v_add_f32_dpp v168, v168, v168 row_half_mirror row_mask:0xf bank_mask:0xf bound_ctrl:1
	v_pk_fma_f32 v[132:133], v[34:35], v[62:63], v[132:133]
	v_fma_f32 v136, v166, v108, v168
	v_pk_fma_f32 v[36:37], v[64:65], v[166:167], v[126:127] op_sel_hi:[1,0,1]
	v_pk_fma_f32 v[38:39], v[66:67], v[166:167], v[128:129] op_sel_hi:[1,0,1]
	v_pk_fma_f32 v[32:33], v[68:69], v[166:167], v[130:131] op_sel_hi:[1,0,1]
	v_pk_fma_f32 v[34:35], v[70:71], v[166:167], v[132:133] op_sel_hi:[1,0,1]
	v_fma_f32 v136, v94, v109, v136
	ds_write_b32 v95, v136 offset:1792
	s_waitcnt lgkmcnt(0)
	v_pk_mul_f32 v[122:123], v[38:39], v[192:193]
	v_pk_mul_f32 v[124:125], v[38:39], v[200:201]
	v_pk_fma_f32 v[122:123], v[36:37], v[190:191], v[122:123]
	v_pk_fma_f32 v[124:125], v[36:37], v[198:199], v[124:125]
	v_pk_fma_f32 v[122:123], v[32:33], v[194:195], v[122:123]
	v_pk_fma_f32 v[124:125], v[32:33], v[202:203], v[124:125]
	v_pk_fma_f32 v[122:123], v[34:35], v[196:197], v[122:123]
	v_pk_fma_f32 v[124:125], v[34:35], v[204:205], v[124:125]
	v_pk_mul_f32 v[126:127], v[222:223], v[230:231] op_sel_hi:[1,0]
	v_add_f32_e32 v166, v122, v123
	v_add_f32_e32 v168, v124, v125
	v_pk_mul_f32 v[128:129], v[224:225], v[230:231] op_sel_hi:[1,0]
	v_pk_mul_f32 v[130:131], v[226:227], v[230:231] op_sel_hi:[1,0]
	v_add_f32_dpp v166, v166, v166 quad_perm:[1,0,3,2] row_mask:0xf bank_mask:0xf bound_ctrl:1
	v_add_f32_dpp v168, v168, v168 quad_perm:[1,0,3,2] row_mask:0xf bank_mask:0xf bound_ctrl:1
	v_pk_mul_f32 v[132:133], v[228:229], v[230:231] op_sel_hi:[1,0]
	v_pk_fma_f32 v[126:127], v[36:37], v[206:207], v[126:127]
	v_add_f32_dpp v166, v166, v166 quad_perm:[2,3,0,1] row_mask:0xf bank_mask:0xf bound_ctrl:1
	v_add_f32_dpp v168, v168, v168 quad_perm:[2,3,0,1] row_mask:0xf bank_mask:0xf bound_ctrl:1
	v_pk_fma_f32 v[128:129], v[38:39], v[208:209], v[128:129]
	v_pk_fma_f32 v[130:131], v[32:33], v[210:211], v[130:131]
	v_add_f32_dpp v166, v166, v166 row_half_mirror row_mask:0xf bank_mask:0xf bound_ctrl:1
	v_add_f32_dpp v168, v168, v168 row_half_mirror row_mask:0xf bank_mask:0xf bound_ctrl:1
	v_pk_fma_f32 v[132:133], v[34:35], v[212:213], v[132:133]
	v_fma_f32 v136, v166, v232, v168
	v_pk_fma_f32 v[36:37], v[214:215], v[166:167], v[126:127] op_sel_hi:[1,0,1]
	v_pk_fma_f32 v[38:39], v[216:217], v[166:167], v[128:129] op_sel_hi:[1,0,1]
	v_pk_fma_f32 v[32:33], v[218:219], v[166:167], v[130:131] op_sel_hi:[1,0,1]
	v_pk_fma_f32 v[34:35], v[220:221], v[166:167], v[132:133] op_sel_hi:[1,0,1]
	v_fma_f32 v136, v230, v233, v136
	ds_write_b32 v95, v136 offset:1920
	s_add_i32 s24, s24, 1
	s_branch .LBB0_1524
